# in-projection phase fully rewritten (128x128 tiles, full-line DMA ring, dwordx4 epilogues incl. gated zv and bf16 zfnP)
# speedup vs baseline: 1.2196x; 1.0172x over previous
; __device__ __forceinline__ int otid() { int t = threadIdx.x; asm volatile("" : "+v"(t)); return t; }
; __device__ __forceinline__ bool swz_tile(int r, int TM, int TN, int SR, int SC, int& tm, int& tn) {
;   int b = blockIdx.x;
;   int x = b & 7, j = b >> 3;
;   int nsc = (TN + SC - 1) / SC, nsr = (TM + SR - 1) / SR;
;   int s = r * 8 + x;
;   if (s >= nsr * nsc || j >= SR * SC) return false;
;   int sr = s / nsc, sc = s - sr * nsc;
;   tm = sr * SR + j / SC;
;   tn = sc * SC + j % SC;
;   return tm < TM && tn < TN;
; }
; __device__ __forceinline__ int swz_rounds(int TM, int TN, int SR, int SC) {
;   int nsc = (TN + SC - 1) / SC, nsr = (TM + SR - 1) / SR;
;   return (nsr * nsc + 7) / 8;
; }
; __device__ void phase_inproj(CParams& p, int l, int tm, int tn, char* smem) {
;   const int tid = otid();
;   bf16_t* sA = (bf16_t*)smem;
;   bf16_t* sB = sA + 128 * LDSS;
;   const bool lat = tm < 128;
;   const int tbase = lat ? ((tm >> 6) * 8192 + (tm & 63)) : tm * 128;
;   const int tstr = lat ? 64 : 1;
;   f32x4 acc[4][4];
;   zero_acc<4>(acc);
;   gemm_mainloop<4>(p.hbuf + (size_t)tbase * DM, DM * tstr, p.WinT + ((size_t)l * 1280 + tn * 128) * 1024, 1024, 1024, sA, sB, acc, tid);
.LBB0_311:
	s_or_b64 exec, exec, s[22:23]
	s_xor_b64 s[0:1], s[20:21], -1
	s_mov_b64 s[20:21], s[34:35]
	s_waitcnt lgkmcnt(0)
	s_barrier
	v_writelane_b32 v224, s0, 28
	v_writelane_b32 v224, s1, 29
	s_mov_b64 exec, -1
	v_readlane_b32 s29, v225, 4
	v_readlane_b32 s28, v224, 26
	s_nop 3
	s_lshr_b32 s55, s29, 3
	s_cmp_ge_u32 s55, 60
	s_cbranch_scc1 .Linpj_end
	ds_read_b128 v[252:255], v145 offset:40960
	s_load_dwordx2 s[0:1], s[20:21], 0x150
	s_load_dwordx2 s[6:7], s[20:21], 0x100
	v_readfirstlane_b32 s53, v147
	v_and_b32_e32 v166, 63, v147
	s_mul_i32 s32, s55, 205
	s_lshr_b32 s32, s32, 11
	s_mul_i32 s56, s32, 10
	s_sub_u32 s10, s55, s56
	s_and_b32 s29, s29, 7
	s_cmp_lt_u32 s29, 6
	s_cselect_b32 s52, 3, 2
	s_lshr_b32 s53, s53, 6
	s_lshl_b32 s40, s53, 12
	v_lshrrev_b32_e32 v167, 3, v166
	s_lshl_b32 s57, s53, 5
	v_add_u32_e32 v132, s57, v167
	v_add_u32_e32 v133, 8, v132
	v_add_u32_e32 v134, 16, v132
	v_add_u32_e32 v135, 24, v132
	v_and_b32_e32 v226, 7, v166
	v_lshrrev_b32_e32 v227, 4, v166
	v_xor_b32_e32 v226, v226, v227
	v_lshlrev_b32_e32 v136, 4, v226
	v_xor_b32_e32 v137, 64, v136
	v_lshl_add_u32 v240, v132, 11, v136
	v_lshl_add_u32 v241, v133, 11, v137
	v_lshl_add_u32 v242, v134, 11, v136
	v_lshl_add_u32 v243, v135, 11, v137
	v_and_b32_e32 v167, 15, v166
	v_lshrrev_b32_e32 v227, 4, v166
	s_lshr_b32 s57, s53, 1
	s_and_b32 s58, s53, 1
	s_lshl_b32 s57, s57, 6
	s_lshl_b32 s58, s58, 6
	v_lshrrev_b32_e32 v226, 1, v167
	v_xor_b32_e32 v226, v227, v226
	v_lshlrev_b32_e32 v226, 4, v226
	v_add_u32_e32 v138, s57, v167
	v_lshl_add_u32 v248, v138, 7, v226
	v_xor_b32_e32 v249, 64, v248
	v_add_u32_e32 v250, s58, v167
	v_lshl_add_u32 v250, v250, 7, v226
	v_xor_b32_e32 v251, 64, v250
	v_lshl_add_u32 v139, v227, 2, s58
	v_lshlrev_b32_e32 v141, 1, v139
	v_lshl_add_u32 v141, v138, 9, v141
	v_lshlrev_b32_e32 v139, 2, v139
	s_lshr_b32 s58, s58, 1
	v_lshl_add_u32 v140, v227, 2, s58
	v_lshlrev_b32_e32 v140, 2, v140
	s_mov_b32 s59, 0x0
	s_mov_b32 s62, 0x4000
	s_mov_b32 s63, 0x8000
	s_mov_b32 s92, 0xc000
	s_mov_b32 s93, 0x10000
	s_waitcnt lgkmcnt(0)
	s_mul_i32 s55, s28, 1280
	s_lshl_b32 s56, s10, 7
	s_add_u32 s55, s55, s56
	s_lshl_b32 s55, s55, 11
	s_add_u32 s6, s6, s55
	s_addc_u32 s7, s7, 0
	s_mov_b64 s[12:13], s[6:7]
	s_mov_b32 s41, 0
	s_lshl_b32 s55, s41, 3
	s_add_u32 s55, s55, s29
	s_mul_i32 s55, s55, 6
	s_add_u32 s4, s55, s32
	s_lshr_b32 s55, s4, 6
	s_lshl_b32 s55, s55, 13
	s_and_b32 s56, s4, 63
	s_or_b32 s55, s55, s56
	s_lshl_b32 s56, s4, 7
	s_cmp_lt_u32 s4, 128
	s_cselect_b32 s55, s55, s56
	s_cselect_b32 s98, 17, 11
	s_lshl_b32 s55, s55, 11
	s_add_u32 s8, s0, s55
	s_addc_u32 s9, s1, 0
	v_lshl_add_u32 v236, v132, s98, v136
	v_lshl_add_u32 v237, v133, s98, v137
	v_lshl_add_u32 v238, v134, s98, v136
	v_lshl_add_u32 v239, v135, s98, v137
	s_barrier
	s_add_u32 s54, s40, s59
	s_add_u32 m0, s54, 0x0
	s_nop 0
	global_load_lds_dwordx4 v236, s[8:9]
	s_add_u32 m0, s54, 0x400
	s_nop 0
	global_load_lds_dwordx4 v237, s[8:9]
	s_add_u32 m0, s54, 0x800
	s_nop 0
	global_load_lds_dwordx4 v238, s[8:9]
	s_add_u32 m0, s54, 0xc00
	s_nop 0
	global_load_lds_dwordx4 v239, s[8:9]
	s_add_u32 s8, s8, 128
	s_addc_u32 s9, s9, 0
	s_add_u32 s54, s40, s62
	s_add_u32 m0, s54, 0x0
	s_nop 0
	global_load_lds_dwordx4 v240, s[12:13]
	s_add_u32 m0, s54, 0x400
	s_nop 0
	global_load_lds_dwordx4 v241, s[12:13]
	s_add_u32 m0, s54, 0x800
	s_nop 0
	global_load_lds_dwordx4 v242, s[12:13]
	s_add_u32 m0, s54, 0xc00
	s_nop 0
	global_load_lds_dwordx4 v243, s[12:13]
	s_add_u32 s12, s12, 128
	s_addc_u32 s13, s13, 0
	s_add_u32 s54, s40, s63
	s_add_u32 m0, s54, 0x0
	s_nop 0
	global_load_lds_dwordx4 v236, s[8:9]
	s_add_u32 m0, s54, 0x400
	s_nop 0
	global_load_lds_dwordx4 v237, s[8:9]
	s_add_u32 m0, s54, 0x800
	s_nop 0
	global_load_lds_dwordx4 v238, s[8:9]
	s_add_u32 m0, s54, 0xc00
	s_nop 0
	global_load_lds_dwordx4 v239, s[8:9]
	s_add_u32 s8, s8, 128
	s_addc_u32 s9, s9, 0
	s_add_u32 s54, s40, s92
	s_add_u32 m0, s54, 0x0
	s_nop 0
	global_load_lds_dwordx4 v240, s[12:13]
	s_add_u32 m0, s54, 0x400
	s_nop 0
	global_load_lds_dwordx4 v241, s[12:13]
	s_add_u32 m0, s54, 0x800
	s_nop 0
	global_load_lds_dwordx4 v242, s[12:13]
	s_add_u32 m0, s54, 0xc00
	s_nop 0
	global_load_lds_dwordx4 v243, s[12:13]
	s_add_u32 s12, s12, 128
	s_addc_u32 s13, s13, 0
	v_mov_b32_e32 v0, 0
	v_mov_b32_e32 v1, 0
	v_mov_b32_e32 v2, 0
	v_mov_b32_e32 v3, 0
	v_mov_b32_e32 v4, 0
	v_mov_b32_e32 v5, 0
	v_mov_b32_e32 v6, 0
	v_mov_b32_e32 v7, 0
	v_mov_b32_e32 v8, 0
	v_mov_b32_e32 v9, 0
	v_mov_b32_e32 v10, 0
	v_mov_b32_e32 v11, 0
	v_mov_b32_e32 v12, 0
	v_mov_b32_e32 v13, 0
	v_mov_b32_e32 v14, 0
	v_mov_b32_e32 v15, 0
	v_mov_b32_e32 v16, 0
	v_mov_b32_e32 v17, 0
	v_mov_b32_e32 v18, 0
	v_mov_b32_e32 v19, 0
	v_mov_b32_e32 v20, 0
	v_mov_b32_e32 v21, 0
	v_mov_b32_e32 v22, 0
	v_mov_b32_e32 v23, 0
	v_mov_b32_e32 v24, 0
	v_mov_b32_e32 v25, 0
	v_mov_b32_e32 v26, 0
	v_mov_b32_e32 v27, 0
	v_mov_b32_e32 v28, 0
	v_mov_b32_e32 v29, 0
	v_mov_b32_e32 v30, 0
	v_mov_b32_e32 v31, 0
	v_mov_b32_e32 v32, 0
	v_mov_b32_e32 v33, 0
	v_mov_b32_e32 v34, 0
	v_mov_b32_e32 v35, 0
	v_mov_b32_e32 v36, 0
	v_mov_b32_e32 v37, 0
	v_mov_b32_e32 v38, 0
	v_mov_b32_e32 v39, 0
	v_mov_b32_e32 v40, 0
	v_mov_b32_e32 v41, 0
	v_mov_b32_e32 v42, 0
	v_mov_b32_e32 v43, 0
	v_mov_b32_e32 v44, 0
	v_mov_b32_e32 v45, 0
	v_mov_b32_e32 v46, 0
	v_mov_b32_e32 v47, 0
	v_mov_b32_e32 v48, 0
	v_mov_b32_e32 v49, 0
	v_mov_b32_e32 v50, 0
	v_mov_b32_e32 v51, 0
	v_mov_b32_e32 v52, 0
	v_mov_b32_e32 v53, 0
	v_mov_b32_e32 v54, 0
	v_mov_b32_e32 v55, 0
	v_mov_b32_e32 v56, 0
	v_mov_b32_e32 v57, 0
	v_mov_b32_e32 v58, 0
	v_mov_b32_e32 v59, 0
	v_mov_b32_e32 v60, 0
	v_mov_b32_e32 v61, 0
	v_mov_b32_e32 v62, 0
	v_mov_b32_e32 v63, 0
	s_waitcnt vmcnt(8)
	s_barrier
	v_add_u32_e32 v128, s59, v248
	v_add_u32_e32 v130, s62, v250
	ds_read_b128 v[168:171], v128 offset:0
	ds_read_b128 v[184:187], v130 offset:0
	ds_read_b128 v[172:175], v128 offset:2048
	ds_read_b128 v[188:191], v130 offset:2048
	ds_read_b128 v[176:179], v128 offset:4096
	ds_read_b128 v[192:195], v130 offset:4096
	ds_read_b128 v[180:183], v128 offset:6144
	ds_read_b128 v[196:199], v130 offset:6144
; template <int NI> ...
;     ...
;   for (int kt = 0; kt < nk; kt += 2) {
;     G_LOAD(a0, b0, min((kt + 2) * 32, klast));
;     G_COMPUTE(0);
;     G_WRITE(a1, b1, 1);
;     __syncthreads();
;     G_LOAD(a1, b1, min((kt + 3) * 32, klast));
;     G_COMPUTE(1);
;     G_WRITE(a0, b0, 0);
;     __syncthreads();
;   }
; __device__ void phase_inproj(CParams& p, int l, int tm, int tn, char* smem) {
;     ...
;   if (tn < 6) {
;     int cb = (tn & 1) * 128;
;     if (lat && (tn == 2 || tn == 3)) {
;       EPI_LOOP({ p.zfnP[(size_t)(tm * 128 + rl) * 256 + cb + cl] = f2bf(acc[mi][ni][j]); })
;     } else {
;       float* dst = tn < 2 ? p.zs5 : (tn < 4 ? p.zfn : p.zpl);
;       EPI_LOOP({ dst[(size_t)(tbase + rl * tstr) * 256 + cb + cl] = acc[mi][ni][j]; })
;     }
.Linpj_tile:
	s_mov_b32 s2, s4
	s_add_u32 s58, s41, 1
	s_sub_u32 s57, s52, 1
	s_min_u32 s58, s58, s57
	s_lshl_b32 s55, s58, 3
	s_add_u32 s55, s55, s29
	s_mul_i32 s55, s55, 6
	s_add_u32 s4, s55, s32
	s_lshr_b32 s55, s4, 6
	s_lshl_b32 s55, s55, 13
	s_and_b32 s56, s4, 63
	s_or_b32 s55, s55, s56
	s_lshl_b32 s56, s4, 7
	s_cmp_lt_u32 s4, 128
	s_cselect_b32 s55, s55, s56
	s_cselect_b32 s99, 17, 11
	s_lshl_b32 s55, s55, 11
	s_add_u32 s18, s0, s55
	s_addc_u32 s19, s1, 0
	s_mov_b32 s53, 0
.Linpj_pair:
	s_waitcnt lgkmcnt(0)
	s_cmp_eq_u32 s53, 14
	s_cselect_b64 s[8:9], s[18:19], s[8:9]
	s_cselect_b32 s98, s99, s98
	v_lshl_add_u32 v236, v132, s98, v136
	v_lshl_add_u32 v237, v133, s98, v137
	v_lshl_add_u32 v238, v134, s98, v136
	v_lshl_add_u32 v239, v135, s98, v137
	s_add_u32 s54, s40, s93
	s_add_u32 m0, s54, 0x0
	s_nop 0
	global_load_lds_dwordx4 v236, s[8:9]
	s_add_u32 m0, s54, 0x400
	s_nop 0
	global_load_lds_dwordx4 v237, s[8:9]
	s_add_u32 m0, s54, 0x800
	s_nop 0
	global_load_lds_dwordx4 v238, s[8:9]
	s_add_u32 m0, s54, 0xc00
	s_nop 0
	global_load_lds_dwordx4 v239, s[8:9]
	s_add_u32 s8, s8, 128
	s_addc_u32 s9, s9, 0
	v_add_u32_e32 v129, s59, v249
	v_add_u32_e32 v131, s62, v251
	v_mfma_f32_16x16x32_bf16 v[0:3], v[184:187], v[168:171], v[0:3]
	ds_read_b128 v[200:203], v129 offset:0
	v_mfma_f32_16x16x32_bf16 v[4:7], v[188:191], v[168:171], v[4:7]
	ds_read_b128 v[216:219], v131 offset:0
	v_mfma_f32_16x16x32_bf16 v[8:11], v[192:195], v[168:171], v[8:11]
	ds_read_b128 v[204:207], v129 offset:2048
	v_mfma_f32_16x16x32_bf16 v[12:15], v[196:199], v[168:171], v[12:15]
	ds_read_b128 v[220:223], v131 offset:2048
	v_mfma_f32_16x16x32_bf16 v[16:19], v[184:187], v[172:175], v[16:19]
	ds_read_b128 v[208:211], v129 offset:4096
	v_mfma_f32_16x16x32_bf16 v[20:23], v[188:191], v[172:175], v[20:23]
	ds_read_b128 v[228:231], v131 offset:4096
	v_mfma_f32_16x16x32_bf16 v[24:27], v[192:195], v[172:175], v[24:27]
	ds_read_b128 v[212:215], v129 offset:6144
	v_mfma_f32_16x16x32_bf16 v[28:31], v[196:199], v[172:175], v[28:31]
	ds_read_b128 v[232:235], v131 offset:6144
	v_mfma_f32_16x16x32_bf16 v[32:35], v[184:187], v[176:179], v[32:35]
	v_mfma_f32_16x16x32_bf16 v[36:39], v[188:191], v[176:179], v[36:39]
	v_mfma_f32_16x16x32_bf16 v[40:43], v[192:195], v[176:179], v[40:43]
	v_mfma_f32_16x16x32_bf16 v[44:47], v[196:199], v[176:179], v[44:47]
	v_mfma_f32_16x16x32_bf16 v[48:51], v[184:187], v[180:183], v[48:51]
	v_mfma_f32_16x16x32_bf16 v[52:55], v[188:191], v[180:183], v[52:55]
	v_mfma_f32_16x16x32_bf16 v[56:59], v[192:195], v[180:183], v[56:59]
	v_mfma_f32_16x16x32_bf16 v[60:63], v[196:199], v[180:183], v[60:63]
	s_waitcnt vmcnt(4) lgkmcnt(0)
	s_barrier
	s_cmp_eq_u32 s53, 14
	s_cselect_b64 s[12:13], s[6:7], s[12:13]
	s_add_u32 s54, s40, s59
	s_add_u32 m0, s54, 0x0
	s_nop 0
	global_load_lds_dwordx4 v240, s[12:13]
	s_add_u32 m0, s54, 0x400
	s_nop 0
	global_load_lds_dwordx4 v241, s[12:13]
	s_add_u32 m0, s54, 0x800
	s_nop 0
	global_load_lds_dwordx4 v242, s[12:13]
	s_add_u32 m0, s54, 0xc00
	s_nop 0
	global_load_lds_dwordx4 v243, s[12:13]
	s_add_u32 s12, s12, 128
	s_addc_u32 s13, s13, 0
	v_add_u32_e32 v128, s63, v248
	v_add_u32_e32 v130, s92, v250
	v_mfma_f32_16x16x32_bf16 v[0:3], v[216:219], v[200:203], v[0:3]
	ds_read_b128 v[168:171], v128 offset:0
	v_mfma_f32_16x16x32_bf16 v[4:7], v[220:223], v[200:203], v[4:7]
	ds_read_b128 v[184:187], v130 offset:0
	v_mfma_f32_16x16x32_bf16 v[8:11], v[228:231], v[200:203], v[8:11]
	ds_read_b128 v[172:175], v128 offset:2048
	v_mfma_f32_16x16x32_bf16 v[12:15], v[232:235], v[200:203], v[12:15]
	ds_read_b128 v[188:191], v130 offset:2048
	v_mfma_f32_16x16x32_bf16 v[16:19], v[216:219], v[204:207], v[16:19]
	ds_read_b128 v[176:179], v128 offset:4096
	v_mfma_f32_16x16x32_bf16 v[20:23], v[220:223], v[204:207], v[20:23]
	ds_read_b128 v[192:195], v130 offset:4096
	v_mfma_f32_16x16x32_bf16 v[24:27], v[228:231], v[204:207], v[24:27]
	ds_read_b128 v[180:183], v128 offset:6144
	v_mfma_f32_16x16x32_bf16 v[28:31], v[232:235], v[204:207], v[28:31]
	ds_read_b128 v[196:199], v130 offset:6144
	v_mfma_f32_16x16x32_bf16 v[32:35], v[216:219], v[208:211], v[32:35]
	v_mfma_f32_16x16x32_bf16 v[36:39], v[220:223], v[208:211], v[36:39]
	v_mfma_f32_16x16x32_bf16 v[40:43], v[228:231], v[208:211], v[40:43]
	v_mfma_f32_16x16x32_bf16 v[44:47], v[232:235], v[208:211], v[44:47]
	v_mfma_f32_16x16x32_bf16 v[48:51], v[216:219], v[212:215], v[48:51]
	v_mfma_f32_16x16x32_bf16 v[52:55], v[220:223], v[212:215], v[52:55]
	v_mfma_f32_16x16x32_bf16 v[56:59], v[228:231], v[212:215], v[56:59]
	v_mfma_f32_16x16x32_bf16 v[60:63], v[232:235], v[212:215], v[60:63]
	s_mov_b32 s55, s59
	s_mov_b32 s56, s62
	s_mov_b32 s59, s63
	s_mov_b32 s62, s92
	s_mov_b32 s63, s93
	s_mov_b32 s92, s55
	s_mov_b32 s93, s56
	s_add_u32 s53, s53, 1
	s_cmp_lt_u32 s53, 16
	s_cbranch_scc1 .Linpj_pair
	s_lshr_b32 s55, s2, 6
	s_lshl_b32 s55, s55, 13
	s_and_b32 s56, s2, 63
	s_or_b32 s55, s55, s56
	s_lshl_b32 s56, s2, 7
	s_cmp_lt_u32 s2, 128
	s_cselect_b32 s55, s55, s56
	s_cselect_b32 s28, 16, 10
	s_cselect_b32 s58, 1, 0
	s_lshl_b32 s55, s55, 10
	s_cmp_ge_u32 s10, 6
	s_cbranch_scc1 .Linpj_egate
	s_lshr_b32 s56, s10, 1
	s_cmp_eq_u32 s56, 1
	s_cselect_b32 s58, s58, 0
	s_lshl_b32 s56, s56, 3
	s_add_u32 s56, s56, 0x190
	s_cmp_eq_u32 s58, 1
	s_cselect_b32 s56, 0x1e8, s56
	s_load_dwordx2 s[24:25], s[20:21], s56
	s_and_b32 s57, s10, 1
	s_cmp_eq_u32 s58, 1
	s_cbranch_scc1 .Linpj_ebf16
	s_lshl_b32 s57, s57, 9
	s_add_u32 s55, s55, s57
	v_lshl_add_u32 v142, v138, s28, v139
	s_lshl_b32 s57, 16, s28
	s_nop 15
	s_nop 7
	s_waitcnt lgkmcnt(0)
	s_add_u32 s22, s24, s55
	s_addc_u32 s23, s25, 0
	global_store_dwordx4 v142, v[0:3], s[22:23] offset:0
	global_store_dwordx4 v142, v[4:7], s[22:23] offset:64
	global_store_dwordx4 v142, v[8:11], s[22:23] offset:128
	global_store_dwordx4 v142, v[12:15], s[22:23] offset:192
	s_add_u32 s22, s22, s57
	s_addc_u32 s23, s23, 0
	global_store_dwordx4 v142, v[16:19], s[22:23] offset:0
	global_store_dwordx4 v142, v[20:23], s[22:23] offset:64
	global_store_dwordx4 v142, v[24:27], s[22:23] offset:128
	global_store_dwordx4 v142, v[28:31], s[22:23] offset:192
	s_add_u32 s22, s22, s57
	s_addc_u32 s23, s23, 0
	global_store_dwordx4 v142, v[32:35], s[22:23] offset:0
	global_store_dwordx4 v142, v[36:39], s[22:23] offset:64
	global_store_dwordx4 v142, v[40:43], s[22:23] offset:128
	global_store_dwordx4 v142, v[44:47], s[22:23] offset:192
	s_add_u32 s22, s22, s57
	s_addc_u32 s23, s23, 0
	global_store_dwordx4 v142, v[48:51], s[22:23] offset:0
	global_store_dwordx4 v142, v[52:55], s[22:23] offset:64
	global_store_dwordx4 v142, v[56:59], s[22:23] offset:128
	global_store_dwordx4 v142, v[60:63], s[22:23] offset:192
	s_branch .Linpj_edone
; __device__ __forceinline__ float sigmoidf_(float v) { return 1.f / (1.f + __expf(-v)); }
; __device__ void phase_inproj(CParams& p, int l, int tm, int tn, char* smem) {
;     ...
;   if (tn < 6) {
;     int cb = (tn & 1) * 128;
;     if (lat && (tn == 2 || tn == 3)) {
;       EPI_LOOP({ p.zfnP[(size_t)(tm * 128 + rl) * 256 + cb + cl] = f2bf(acc[mi][ni][j]); })
;     } else {
;       float* dst = tn < 2 ? p.zs5 : (tn < 4 ? p.zfn : p.zpl);
;       EPI_LOOP({ dst[(size_t)(tbase + rl * tstr) * 256 + cb + cl] = acc[mi][ni][j]; })
;     }
;   } else {
;     int T = tn - 6;
;     const int lane = tid & 63, wid = tid >> 6, wr = wid >> 1, wc = wid & 1;
; #pragma unroll
;     for (int mi = 0; mi < 4; mi++)
; #pragma unroll
;       for (int a = 0; a < 2; a++)
; #pragma unroll
;         for (int j = 0; j < 4; j++) {
;           int rl = wr * 64 + mi * 16 + (lane >> 4) * 4 + j;
;           int ch = T * 64 + wc * 32 + a * 16 + (lane & 15);
;           float val = acc[mi][2 * a][j], gt = acc[mi][2 * a + 1][j];
;           p.zv[(size_t)(tbase + rl * tstr) * 256 + ch] = val * sigmoidf_(gt);
;         }
.Linpj_ebf16:
	s_lshl_b32 s57, s57, 8
	s_lshl_b32 s55, s2, 16
	s_add_u32 s55, s55, s57
	s_nop 15
	s_nop 7
	s_waitcnt lgkmcnt(0)
	s_add_u32 s22, s24, s55
	s_addc_u32 s23, s25, 0
	v_cvt_pk_bf16_f32 v64, v0, v1
	v_cvt_pk_bf16_f32 v65, v2, v3
	global_store_dwordx2 v141, v[64:65], s[22:23] offset:0
	v_cvt_pk_bf16_f32 v66, v4, v5
	v_cvt_pk_bf16_f32 v67, v6, v7
	global_store_dwordx2 v141, v[66:67], s[22:23] offset:32
	v_cvt_pk_bf16_f32 v68, v8, v9
	v_cvt_pk_bf16_f32 v69, v10, v11
	global_store_dwordx2 v141, v[68:69], s[22:23] offset:64
	v_cvt_pk_bf16_f32 v70, v12, v13
	v_cvt_pk_bf16_f32 v71, v14, v15
	global_store_dwordx2 v141, v[70:71], s[22:23] offset:96
	s_add_u32 s22, s22, 0x2000
	s_addc_u32 s23, s23, 0
	v_cvt_pk_bf16_f32 v72, v16, v17
	v_cvt_pk_bf16_f32 v73, v18, v19
	global_store_dwordx2 v141, v[72:73], s[22:23] offset:0
	v_cvt_pk_bf16_f32 v74, v20, v21
	v_cvt_pk_bf16_f32 v75, v22, v23
	global_store_dwordx2 v141, v[74:75], s[22:23] offset:32
	v_cvt_pk_bf16_f32 v76, v24, v25
	v_cvt_pk_bf16_f32 v77, v26, v27
	global_store_dwordx2 v141, v[76:77], s[22:23] offset:64
	v_cvt_pk_bf16_f32 v78, v28, v29
	v_cvt_pk_bf16_f32 v79, v30, v31
	global_store_dwordx2 v141, v[78:79], s[22:23] offset:96
	s_add_u32 s22, s22, 0x2000
	s_addc_u32 s23, s23, 0
	v_cvt_pk_bf16_f32 v80, v32, v33
	v_cvt_pk_bf16_f32 v81, v34, v35
	global_store_dwordx2 v141, v[80:81], s[22:23] offset:0
	v_cvt_pk_bf16_f32 v82, v36, v37
	v_cvt_pk_bf16_f32 v83, v38, v39
	global_store_dwordx2 v141, v[82:83], s[22:23] offset:32
	v_cvt_pk_bf16_f32 v84, v40, v41
	v_cvt_pk_bf16_f32 v85, v42, v43
	global_store_dwordx2 v141, v[84:85], s[22:23] offset:64
	v_cvt_pk_bf16_f32 v86, v44, v45
	v_cvt_pk_bf16_f32 v87, v46, v47
	global_store_dwordx2 v141, v[86:87], s[22:23] offset:96
	s_add_u32 s22, s22, 0x2000
	s_addc_u32 s23, s23, 0
	v_cvt_pk_bf16_f32 v88, v48, v49
	v_cvt_pk_bf16_f32 v89, v50, v51
	global_store_dwordx2 v141, v[88:89], s[22:23] offset:0
	v_cvt_pk_bf16_f32 v90, v52, v53
	v_cvt_pk_bf16_f32 v91, v54, v55
	global_store_dwordx2 v141, v[90:91], s[22:23] offset:32
	v_cvt_pk_bf16_f32 v92, v56, v57
	v_cvt_pk_bf16_f32 v93, v58, v59
	global_store_dwordx2 v141, v[92:93], s[22:23] offset:64
	v_cvt_pk_bf16_f32 v94, v60, v61
	v_cvt_pk_bf16_f32 v95, v62, v63
	global_store_dwordx2 v141, v[94:95], s[22:23] offset:96
	s_branch .Linpj_edone
.Linpj_egate:
	s_load_dwordx2 s[24:25], s[20:21], 0x1a8
	s_sub_u32 s57, s10, 6
	s_lshl_b32 s57, s57, 8
	s_add_u32 s55, s55, s57
	v_lshl_add_u32 v142, v138, s28, v140
	s_lshl_b32 s57, 16, s28
	s_nop 15
	s_nop 7
	s_waitcnt lgkmcnt(0)
	s_add_u32 s22, s24, s55
	s_addc_u32 s23, s25, 0
	v_mul_f32_e32 v64, 0xbfb8aa3b, v4
	v_mul_f32_e32 v65, 0xbfb8aa3b, v5
	v_mul_f32_e32 v66, 0xbfb8aa3b, v6
	v_mul_f32_e32 v67, 0xbfb8aa3b, v7
	v_mul_f32_e32 v68, 0xbfb8aa3b, v12
	v_mul_f32_e32 v69, 0xbfb8aa3b, v13
	v_mul_f32_e32 v70, 0xbfb8aa3b, v14
	v_mul_f32_e32 v71, 0xbfb8aa3b, v15
	v_exp_f32_e32 v64, v64
	v_exp_f32_e32 v65, v65
	v_exp_f32_e32 v66, v66
	v_exp_f32_e32 v67, v67
	v_exp_f32_e32 v68, v68
	v_exp_f32_e32 v69, v69
	v_exp_f32_e32 v70, v70
	v_exp_f32_e32 v71, v71
	v_add_f32_e32 v64, 1.0, v64
	v_add_f32_e32 v65, 1.0, v65
	v_add_f32_e32 v66, 1.0, v66
	v_add_f32_e32 v67, 1.0, v67
	v_add_f32_e32 v68, 1.0, v68
	v_add_f32_e32 v69, 1.0, v69
	v_add_f32_e32 v70, 1.0, v70
	v_add_f32_e32 v71, 1.0, v71
	v_rcp_f32_e32 v64, v64
	v_rcp_f32_e32 v65, v65
	v_rcp_f32_e32 v66, v66
	v_rcp_f32_e32 v67, v67
	v_rcp_f32_e32 v68, v68
	v_rcp_f32_e32 v69, v69
	v_rcp_f32_e32 v70, v70
	v_rcp_f32_e32 v71, v71
	v_mul_f32_e32 v64, v64, v0
	v_mul_f32_e32 v65, v65, v1
	v_mul_f32_e32 v66, v66, v2
	v_mul_f32_e32 v67, v67, v3
	v_mul_f32_e32 v68, v68, v8
	v_mul_f32_e32 v69, v69, v9
	v_mul_f32_e32 v70, v70, v10
	v_mul_f32_e32 v71, v71, v11
	global_store_dwordx4 v142, v[64:67], s[22:23] offset:0
	global_store_dwordx4 v142, v[68:71], s[22:23] offset:64
	s_add_u32 s22, s22, s57
	s_addc_u32 s23, s23, 0
	v_mul_f32_e32 v72, 0xbfb8aa3b, v20
	v_mul_f32_e32 v73, 0xbfb8aa3b, v21
	v_mul_f32_e32 v74, 0xbfb8aa3b, v22
	v_mul_f32_e32 v75, 0xbfb8aa3b, v23
	v_mul_f32_e32 v76, 0xbfb8aa3b, v28
	v_mul_f32_e32 v77, 0xbfb8aa3b, v29
	v_mul_f32_e32 v78, 0xbfb8aa3b, v30
	v_mul_f32_e32 v79, 0xbfb8aa3b, v31
	v_exp_f32_e32 v72, v72
	v_exp_f32_e32 v73, v73
	v_exp_f32_e32 v74, v74
	v_exp_f32_e32 v75, v75
	v_exp_f32_e32 v76, v76
	v_exp_f32_e32 v77, v77
	v_exp_f32_e32 v78, v78
	v_exp_f32_e32 v79, v79
	v_add_f32_e32 v72, 1.0, v72
	v_add_f32_e32 v73, 1.0, v73
	v_add_f32_e32 v74, 1.0, v74
	v_add_f32_e32 v75, 1.0, v75
	v_add_f32_e32 v76, 1.0, v76
	v_add_f32_e32 v77, 1.0, v77
	v_add_f32_e32 v78, 1.0, v78
	v_add_f32_e32 v79, 1.0, v79
	v_rcp_f32_e32 v72, v72
	v_rcp_f32_e32 v73, v73
	v_rcp_f32_e32 v74, v74
	v_rcp_f32_e32 v75, v75
	v_rcp_f32_e32 v76, v76
	v_rcp_f32_e32 v77, v77
	v_rcp_f32_e32 v78, v78
	v_rcp_f32_e32 v79, v79
	v_mul_f32_e32 v72, v72, v16
	v_mul_f32_e32 v73, v73, v17
	v_mul_f32_e32 v74, v74, v18
	v_mul_f32_e32 v75, v75, v19
; __device__ __forceinline__ float sigmoidf_(float v) { return 1.f / (1.f + __expf(-v)); }
; __device__ void phase_inproj(CParams& p, int l, int tm, int tn, char* smem) {
;     ...
;   } else {
;     int T = tn - 6;
;     const int lane = tid & 63, wid = tid >> 6, wr = wid >> 1, wc = wid & 1;
; #pragma unroll
;     for (int mi = 0; mi < 4; mi++)
; #pragma unroll
;       for (int a = 0; a < 2; a++)
; #pragma unroll
;         for (int j = 0; j < 4; j++) {
;           int rl = wr * 64 + mi * 16 + (lane >> 4) * 4 + j;
;           int ch = T * 64 + wc * 32 + a * 16 + (lane & 15);
;           float val = acc[mi][2 * a][j], gt = acc[mi][2 * a + 1][j];
;           p.zv[(size_t)(tbase + rl * tstr) * 256 + ch] = val * sigmoidf_(gt);
;         }
;   }
	v_mul_f32_e32 v76, v76, v24
	v_mul_f32_e32 v77, v77, v25
	v_mul_f32_e32 v78, v78, v26
	v_mul_f32_e32 v79, v79, v27
	global_store_dwordx4 v142, v[72:75], s[22:23] offset:0
	global_store_dwordx4 v142, v[76:79], s[22:23] offset:64
	s_add_u32 s22, s22, s57
	s_addc_u32 s23, s23, 0
	v_mul_f32_e32 v80, 0xbfb8aa3b, v36
	v_mul_f32_e32 v81, 0xbfb8aa3b, v37
	v_mul_f32_e32 v82, 0xbfb8aa3b, v38
	v_mul_f32_e32 v83, 0xbfb8aa3b, v39
	v_mul_f32_e32 v84, 0xbfb8aa3b, v44
	v_mul_f32_e32 v85, 0xbfb8aa3b, v45
	v_mul_f32_e32 v86, 0xbfb8aa3b, v46
	v_mul_f32_e32 v87, 0xbfb8aa3b, v47
	v_exp_f32_e32 v80, v80
	v_exp_f32_e32 v81, v81
	v_exp_f32_e32 v82, v82
	v_exp_f32_e32 v83, v83
	v_exp_f32_e32 v84, v84
	v_exp_f32_e32 v85, v85
	v_exp_f32_e32 v86, v86
	v_exp_f32_e32 v87, v87
	v_add_f32_e32 v80, 1.0, v80
	v_add_f32_e32 v81, 1.0, v81
	v_add_f32_e32 v82, 1.0, v82
	v_add_f32_e32 v83, 1.0, v83
	v_add_f32_e32 v84, 1.0, v84
	v_add_f32_e32 v85, 1.0, v85
	v_add_f32_e32 v86, 1.0, v86
	v_add_f32_e32 v87, 1.0, v87
	v_rcp_f32_e32 v80, v80
	v_rcp_f32_e32 v81, v81
	v_rcp_f32_e32 v82, v82
	v_rcp_f32_e32 v83, v83
	v_rcp_f32_e32 v84, v84
	v_rcp_f32_e32 v85, v85
	v_rcp_f32_e32 v86, v86
	v_rcp_f32_e32 v87, v87
	v_mul_f32_e32 v80, v80, v32
	v_mul_f32_e32 v81, v81, v33
	v_mul_f32_e32 v82, v82, v34
	v_mul_f32_e32 v83, v83, v35
	v_mul_f32_e32 v84, v84, v40
	v_mul_f32_e32 v85, v85, v41
	v_mul_f32_e32 v86, v86, v42
	v_mul_f32_e32 v87, v87, v43
	global_store_dwordx4 v142, v[80:83], s[22:23] offset:0
	global_store_dwordx4 v142, v[84:87], s[22:23] offset:64
	s_add_u32 s22, s22, s57
	s_addc_u32 s23, s23, 0
	v_mul_f32_e32 v88, 0xbfb8aa3b, v52
	v_mul_f32_e32 v89, 0xbfb8aa3b, v53
	v_mul_f32_e32 v90, 0xbfb8aa3b, v54
	v_mul_f32_e32 v91, 0xbfb8aa3b, v55
	v_mul_f32_e32 v92, 0xbfb8aa3b, v60
	v_mul_f32_e32 v93, 0xbfb8aa3b, v61
	v_mul_f32_e32 v94, 0xbfb8aa3b, v62
	v_mul_f32_e32 v95, 0xbfb8aa3b, v63
	v_exp_f32_e32 v88, v88
	v_exp_f32_e32 v89, v89
	v_exp_f32_e32 v90, v90
	v_exp_f32_e32 v91, v91
	v_exp_f32_e32 v92, v92
	v_exp_f32_e32 v93, v93
	v_exp_f32_e32 v94, v94
	v_exp_f32_e32 v95, v95
	v_add_f32_e32 v88, 1.0, v88
	v_add_f32_e32 v89, 1.0, v89
	v_add_f32_e32 v90, 1.0, v90
	v_add_f32_e32 v91, 1.0, v91
	v_add_f32_e32 v92, 1.0, v92
	v_add_f32_e32 v93, 1.0, v93
	v_add_f32_e32 v94, 1.0, v94
	v_add_f32_e32 v95, 1.0, v95
	v_rcp_f32_e32 v88, v88
	v_rcp_f32_e32 v89, v89
	v_rcp_f32_e32 v90, v90
	v_rcp_f32_e32 v91, v91
	v_rcp_f32_e32 v92, v92
	v_rcp_f32_e32 v93, v93
	v_rcp_f32_e32 v94, v94
	v_rcp_f32_e32 v95, v95
	v_mul_f32_e32 v88, v88, v48
	v_mul_f32_e32 v89, v89, v49
	v_mul_f32_e32 v90, v90, v50
	v_mul_f32_e32 v91, v91, v51
	v_mul_f32_e32 v92, v92, v56
	v_mul_f32_e32 v93, v93, v57
	v_mul_f32_e32 v94, v94, v58
	v_mul_f32_e32 v95, v95, v59
	global_store_dwordx4 v142, v[88:91], s[22:23] offset:0
	global_store_dwordx4 v142, v[92:95], s[22:23] offset:64
.Linpj_edone:
	s_nop 1
	v_mov_b32_e32 v0, 0
	v_mov_b32_e32 v1, 0
	v_mov_b32_e32 v2, 0
	v_mov_b32_e32 v3, 0
	v_mov_b32_e32 v4, 0
	v_mov_b32_e32 v5, 0
	v_mov_b32_e32 v6, 0
	v_mov_b32_e32 v7, 0
	v_mov_b32_e32 v8, 0
	v_mov_b32_e32 v9, 0
	v_mov_b32_e32 v10, 0
	v_mov_b32_e32 v11, 0
	v_mov_b32_e32 v12, 0
	v_mov_b32_e32 v13, 0
	v_mov_b32_e32 v14, 0
	v_mov_b32_e32 v15, 0
	v_mov_b32_e32 v16, 0
	v_mov_b32_e32 v17, 0
	v_mov_b32_e32 v18, 0
	v_mov_b32_e32 v19, 0
	v_mov_b32_e32 v20, 0
	v_mov_b32_e32 v21, 0
	v_mov_b32_e32 v22, 0
	v_mov_b32_e32 v23, 0
	v_mov_b32_e32 v24, 0
	v_mov_b32_e32 v25, 0
	v_mov_b32_e32 v26, 0
	v_mov_b32_e32 v27, 0
	v_mov_b32_e32 v28, 0
	v_mov_b32_e32 v29, 0
	v_mov_b32_e32 v30, 0
	v_mov_b32_e32 v31, 0
	v_mov_b32_e32 v32, 0
	v_mov_b32_e32 v33, 0
	v_mov_b32_e32 v34, 0
	v_mov_b32_e32 v35, 0
	v_mov_b32_e32 v36, 0
	v_mov_b32_e32 v37, 0
	v_mov_b32_e32 v38, 0
	v_mov_b32_e32 v39, 0
	v_mov_b32_e32 v40, 0
	v_mov_b32_e32 v41, 0
	v_mov_b32_e32 v42, 0
	v_mov_b32_e32 v43, 0
	v_mov_b32_e32 v44, 0
	v_mov_b32_e32 v45, 0
	v_mov_b32_e32 v46, 0
	v_mov_b32_e32 v47, 0
	v_mov_b32_e32 v48, 0
	v_mov_b32_e32 v49, 0
	v_mov_b32_e32 v50, 0
	v_mov_b32_e32 v51, 0
	v_mov_b32_e32 v52, 0
	v_mov_b32_e32 v53, 0
	v_mov_b32_e32 v54, 0
	v_mov_b32_e32 v55, 0
	v_mov_b32_e32 v56, 0
	v_mov_b32_e32 v57, 0
	v_mov_b32_e32 v58, 0
	v_mov_b32_e32 v59, 0
	v_mov_b32_e32 v60, 0
	v_mov_b32_e32 v61, 0
	v_mov_b32_e32 v62, 0
	v_mov_b32_e32 v63, 0
	s_waitcnt vmcnt(0)
	s_add_u32 s41, s41, 1
	s_cmp_lt_u32 s41, s52
	s_cbranch_scc1 .Linpj_tile
	s_waitcnt vmcnt(0) lgkmcnt(0)
	s_barrier
	ds_write_b128 v145, v[252:255] offset:40960
	s_waitcnt lgkmcnt(0)
	s_barrier
.Linpj_end:
.LBB0_324:
	s_waitcnt vmcnt(0)
	s_waitcnt vmcnt(63) expcnt(7) lgkmcnt(15)
	s_barrier
	s_and_saveexec_b64 s[20:21], s[38:39]
	s_movk_i32 s0, 0x4000
	s_cbranch_execz .LBB0_376
	s_waitcnt vmcnt(0) expcnt(0) lgkmcnt(0)
	ds_read_b32 v2, v145 offset:40960
	ds_read_b32 v0, v145 offset:40964
	s_waitcnt lgkmcnt(1)
	v_cmp_ne_u32_e32 vcc, 0, v2
	s_cbranch_vccnz .LBB0_340
	s_mov_b32 s2, 1
	s_branch .LBB0_328
